# PX row-sum wave reduction as DPP moves + permlane swaps instead of six ds_bpermute round trips; on top of the pass2 DPP build
# baseline (speedup 1.0000x reference)
; __device__ __forceinline__ unsigned pk2(float lo, float hi) { const f32x2_t v = {lo, hi}; return __builtin_bit_cast(unsigned, __builtin_convertvector(v, bf16x2_t)); }
; __device__ __forceinline__ float wave_sum(float v) {
; #pragma unroll
;     for (int o = 1; o < 64; o <<= 1) v += __shfl_xor(v, o);
;     return v;
; }
; __device__ __forceinline__ void px_phase(const float* x, bf16* XB, float* SS, int M, int wave, int lane) {
;     ...
;     for (int m0 = gw; m0 < M; m0 += 2 * NGW) {
;         const int m1 = m0 + NGW; const bool two = m1 < M;
;         const f32x4* xa = (const f32x4*)(x + (size_t)m0 * D) + lane; const f32x4* xb = (const f32x4*)(x + (size_t)(two ? m1 : m0) * D) + lane;
;         f32x4 va[4], vb[4]; float sa = 0.f, sb = 0.f;
; #pragma unroll
;         for (int j = 0; j < 4; ++j) { va[j] = xa[64 * j]; vb[j] = xb[64 * j]; }
; #pragma unroll
;         for (int j = 0; j < 4; ++j) { sa += (va[j][0] * va[j][0] + va[j][1] * va[j][1]) + (va[j][2] * va[j][2] + va[j][3] * va[j][3]); sb += (vb[j][0] * vb[j][0] + vb[j][1] * vb[j][1]) + (vb[j][2] * vb[j][2] + vb[j][3] * vb[j][3]); }
;         sa = wave_sum(sa); sb = wave_sum(sb);
;         v2u* oa = (v2u*)(XB + (size_t)m0 * D) + lane;
; #pragma unroll
;         for (int j = 0; j < 4; ++j) { v2u w; w.x = pk2(va[j][0], va[j][1]); w.y = pk2(va[j][2], va[j][3]); oa[64 * j] = w; }
;         if (lane < 16) SS[(size_t)m0 * 16 + lane] = (lane == 0) ? sa : 0.f;
;         if (two) { v2u* ob = (v2u*)(XB + (size_t)m1 * D) + lane;
; #pragma unroll
;             for (int j = 0; j < 4; ++j) { v2u w; w.x = pk2(vb[j][0], vb[j][1]); w.y = pk2(vb[j][2], vb[j][3]); ob[64 * j] = w; }
;             if (lane < 16) SS[(size_t)m1 * 16 + lane] = (lane == 0) ? sb : 0.f; }
.LBB0_625:
	s_ashr_i32 s5, s4, 31
	s_lshl_b64 s[2:3], s[4:5], 12
	v_lshl_add_u64 v[0:1], v[20:21], 0, s[2:3]
	s_add_i32 s2, s4, s80
	s_cmp_lt_i32 s2, s12
	s_cselect_b64 s[6:7], -1, 0
	s_waitcnt lgkmcnt(0)
	global_load_dwordx4 v[32:35], v[0:1], off
	global_load_dwordx4 v[36:39], v[0:1], off offset:1024
	global_load_dwordx4 v[40:43], v[0:1], off offset:2048
	global_load_dwordx4 v[44:47], v[0:1], off offset:3072
	s_and_b64 s[8:9], s[6:7], exec
	s_cselect_b32 s8, s2, s4
	s_ashr_i32 s9, s8, 31
	s_lshl_b64 s[8:9], s[8:9], 12
	v_lshl_add_u64 v[0:1], v[20:21], 0, s[8:9]
	global_load_dwordx4 v[12:15], v[0:1], off
	global_load_dwordx4 v[8:11], v[0:1], off offset:1024
	global_load_dwordx4 v[4:7], v[0:1], off offset:2048
	s_nop 0
	global_load_dwordx4 v[0:3], v[0:1], off offset:3072
	s_lshl_b64 s[8:9], s[4:5], 11
	s_waitcnt vmcnt(7)
	v_mul_f32_e32 v48, v33, v33
	v_mul_f32_e32 v49, v35, v35
	s_waitcnt vmcnt(6)
	v_mul_f32_e32 v50, v37, v37
	v_mul_f32_e32 v51, v39, v39
	s_waitcnt vmcnt(5)
	v_mul_f32_e32 v52, v41, v41
	v_mul_f32_e32 v53, v43, v43
	v_fmac_f32_e32 v48, v32, v32
	v_fmac_f32_e32 v49, v34, v34
	v_fmac_f32_e32 v50, v36, v36
	v_fmac_f32_e32 v51, v38, v38
	s_waitcnt vmcnt(4)
	v_mul_f32_e32 v54, v45, v45
	v_mul_f32_e32 v55, v47, v47
	v_fmac_f32_e32 v52, v40, v40
	v_fmac_f32_e32 v53, v42, v42
	v_add_f32_e32 v48, v48, v49
	v_add_f32_e32 v49, v50, v51
	v_fmac_f32_e32 v54, v44, v44
	v_fmac_f32_e32 v55, v46, v46
	v_add_f32_e32 v50, v52, v53
	v_add_f32_e32 v48, v48, v49
	v_add_f32_e32 v51, v54, v55
	v_add_f32_e32 v48, v48, v50
	v_add_f32_e32 v48, v48, v51
	s_waitcnt vmcnt(3)
	v_mul_f32_e32 v49, v13, v13
	v_mul_f32_e32 v50, v15, v15
	s_waitcnt vmcnt(2)
	v_mul_f32_e32 v51, v9, v9
	v_mul_f32_e32 v52, v11, v11
	s_waitcnt vmcnt(1)
	v_mul_f32_e32 v53, v5, v5
	v_mul_f32_e32 v54, v7, v7
	v_fmac_f32_e32 v49, v12, v12
	v_fmac_f32_e32 v50, v14, v14
	v_fmac_f32_e32 v51, v8, v8
	v_fmac_f32_e32 v52, v10, v10
	s_waitcnt vmcnt(0)
	v_mul_f32_e32 v55, v1, v1
	v_mul_f32_e32 v56, v3, v3
	v_fmac_f32_e32 v53, v4, v4
	v_fmac_f32_e32 v54, v6, v6
	v_add_f32_e32 v49, v49, v50
	v_add_f32_e32 v50, v51, v52
	v_fmac_f32_e32 v55, v0, v0
	v_fmac_f32_e32 v56, v2, v2
	v_add_f32_e32 v51, v53, v54
	v_add_f32_e32 v49, v49, v50
	v_add_f32_e32 v52, v55, v56
	v_add_f32_e32 v49, v49, v51
	v_add_f32_e32 v49, v49, v52
	s_nop 1
	v_mov_b32_dpp v57, v48 quad_perm:[1,0,3,2] row_mask:0xf bank_mask:0xf
	v_mov_b32_dpp v50, v49 quad_perm:[1,0,3,2] row_mask:0xf bank_mask:0xf
	v_cvt_pk_bf16_f32 v32, v32, v33
	v_cvt_pk_bf16_f32 v33, v34, v35
	v_cvt_pk_bf16_f32 v34, v36, v37
	s_waitcnt lgkmcnt(1)
	v_add_f32_e32 v51, v48, v57
	s_waitcnt lgkmcnt(0)
	v_add_f32_e32 v50, v49, v50
	s_nop 1
	v_mov_b32_dpp v52, v51 quad_perm:[2,3,0,1] row_mask:0xf bank_mask:0xf
	v_mov_b32_dpp v53, v50 quad_perm:[2,3,0,1] row_mask:0xf bank_mask:0xf
	v_cvt_pk_bf16_f32 v35, v38, v39
	v_cvt_pk_bf16_f32 v36, v40, v41
	v_lshl_add_u64 v[48:49], v[22:23], 0, s[8:9]
	s_waitcnt lgkmcnt(1)
	v_add_f32_e32 v51, v51, v52
	s_waitcnt lgkmcnt(0)
	v_add_f32_e32 v50, v50, v53
	s_nop 1
	v_mov_b32_dpp v52, v51 row_half_mirror row_mask:0xf bank_mask:0xf
	v_mov_b32_dpp v53, v50 row_half_mirror row_mask:0xf bank_mask:0xf
	global_store_dwordx2 v[48:49], v[32:33], off
	global_store_dwordx2 v[48:49], v[34:35], off offset:512
	s_waitcnt lgkmcnt(1)
	v_add_f32_e32 v37, v51, v52
	s_waitcnt lgkmcnt(0)
	v_add_f32_e32 v50, v50, v53
	s_nop 1
	v_mov_b32_dpp v51, v37 row_mirror row_mask:0xf bank_mask:0xf
	v_mov_b32_dpp v52, v50 row_mirror row_mask:0xf bank_mask:0xf
	s_waitcnt lgkmcnt(1)
	v_add_f32_e32 v37, v37, v51
	s_waitcnt lgkmcnt(0)
	v_add_f32_e32 v39, v50, v52
	v_mov_b32_e32 v38, v37
	v_mov_b32_e32 v40, v39
	s_nop 1
	v_permlane16_swap_b32_e32 v37, v38
	v_permlane16_swap_b32_e32 v39, v40
	s_waitcnt lgkmcnt(1)
	v_add_f32_e32 v34, v37, v38
	s_waitcnt lgkmcnt(0)
	v_add_f32_e32 v32, v39, v40
	v_mov_b32_e32 v35, v34
	v_mov_b32_e32 v33, v32
	s_nop 1
	v_permlane32_swap_b32_e32 v34, v35
	v_permlane32_swap_b32_e32 v32, v33
	v_cvt_pk_bf16_f32 v37, v42, v43
	global_store_dwordx2 v[48:49], v[36:37], off offset:1024
	v_cvt_pk_bf16_f32 v36, v44, v45
	v_cvt_pk_bf16_f32 v37, v46, v47
	global_store_dwordx2 v[48:49], v[36:37], off offset:1536
	s_and_saveexec_b64 s[8:9], s[0:1]
	s_cbranch_execnz .LBB0_627
	s_or_b64 exec, exec, s[8:9]
	s_andn2_b64 vcc, exec, s[6:7]
	s_cbranch_vccnz .LBB0_624
	s_branch .LBB0_628
